# gate epilogue: the two cross-row sums per row group by v_permlane16_swap / v_permlane32_swap adds instead of four dependent ds_bpermute round trips
# speedup vs baseline: 1.0007x; 1.0007x over previous
.LBB0_1251:
	s_waitcnt lgkmcnt(0)
	v_lshl_or_b32 v156, s20, 7, v170
	v_add_u32_e32 v154, s19, v156
	s_lshl_b32 s0, s18, 6
	v_cmp_gt_i32_e32 vcc, s14, v154
	s_or_b32 s18, s0, s6
	v_mov_b64_e32 v[132:133], s[88:89]
	v_cndmask_b32_e32 v130, v168, v154, vcc
	v_mad_i64_i32 v[132:133], s[0:1], v130, s15, v[132:133]
	s_lshl_b32 s6, s18, 1
	s_waitcnt vmcnt(0)
	v_lshl_add_u64 v[132:133], v[132:133], 0, s[6:7]
	v_lshlrev_b32_e32 v0, 3, v169
	s_waitcnt lgkmcnt(0)
	s_barrier
	v_readlane_b32 s36, v192, 0
	v_readlane_b32 s37, v192, 1
	v_lshlrev_b32_e32 v0, 2, v169
	v_or_b32_e32 v0, s18, v0
	v_lshlrev_b32_e32 v254, 1, v0
	v_and_b32_e32 v250, 1, v169
	v_mul_u32_u24_e32 v250, 24, v250
	v_add_u32_e32 v254, v254, v250
	v_lshlrev_b32_e32 v0, 2, v0
	global_load_dwordx4 v[194:197], v0, s[26:27] offset:0
	global_load_dwordx4 v[198:201], v0, s[26:27] offset:64
	global_load_dwordx4 v[202:205], v0, s[26:27] offset:128
	global_load_dwordx4 v[206:209], v0, s[26:27] offset:192
	global_load_dwordx4 v[210:213], v0, s[36:37] offset:0
	global_load_dwordx4 v[214:217], v0, s[36:37] offset:64
	global_load_dwordx4 v[218:221], v0, s[36:37] offset:128
	global_load_dwordx4 v[222:225], v0, s[36:37] offset:192
	v_xor_b32_e32 v255, 16, v167
	v_lshlrev_b32_e32 v255, 2, v255
	v_xor_b32_e32 v193, 32, v167
	v_lshlrev_b32_e32 v193, 2, v193
	v_mov_b32_e32 v0, v156
	s_lshr_b32 s20, s18, 4
	s_mov_b32 s21, 0
	s_add_i32 s0, s19, 0
	v_add_u32_e32 v253, s0, v0
	v_cmp_gt_i32_e32 vcc, s14, v253
	s_nop 1
	v_cndmask_b32_e32 v253, v168, v253, vcc
	v_mov_b64_e32 v[148:149], s[88:89]
	v_mad_i64_i32 v[148:149], s[0:1], v253, s15, v[148:149]
	v_mov_b32_e32 v244, v254
	v_mov_b32_e32 v245, 0
	v_lshl_add_u64 v[148:149], v[148:149], 0, v[244:245]
	global_load_dwordx4 v[130:133], v[148:149], off offset:0
	global_load_dwordx4 v[134:137], v[148:149], off offset:64
	v_ashrrev_i32_e32 v251, 31, v253
	v_mov_b32_e32 v250, v253
	v_lshlrev_b64 v[246:247], 11, v[250:251]
	v_lshl_add_u64 v[246:247], s[54:55], 0, v[246:247]
	v_lshl_add_u64 v[246:247], v[246:247], 0, v[244:245]
	global_load_dwordx4 v[138:141], v[246:247], off offset:0
	global_load_dwordx4 v[142:145], v[246:247], off offset:64
	v_lshlrev_b64 v[246:247], 6, v[250:251]
	v_lshl_add_u64 v[246:247], s[58:59], 0, v[246:247]
	v_lshl_add_u64 v[246:247], v[246:247], 0, s[20:21]
	global_load_dword v146, v[246:247], off
	s_add_i32 s0, s19, 16
	v_add_u32_e32 v253, s0, v0
	v_cmp_gt_i32_e32 vcc, s14, v253
	s_nop 1
	v_cndmask_b32_e32 v253, v168, v253, vcc
	v_mov_b64_e32 v[226:227], s[88:89]
	v_mad_i64_i32 v[226:227], s[0:1], v253, s15, v[226:227]
	v_mov_b32_e32 v244, v254
	v_mov_b32_e32 v245, 0
	v_lshl_add_u64 v[226:227], v[226:227], 0, v[244:245]
	global_load_dwordx4 v[150:153], v[226:227], off offset:0
	global_load_dwordx4 v[154:157], v[226:227], off offset:64
	v_ashrrev_i32_e32 v251, 31, v253
	v_mov_b32_e32 v250, v253
	v_lshlrev_b64 v[246:247], 11, v[250:251]
	v_lshl_add_u64 v[246:247], s[54:55], 0, v[246:247]
	v_lshl_add_u64 v[246:247], v[246:247], 0, v[244:245]
	global_load_dwordx4 v[158:161], v[246:247], off offset:0
	global_load_dwordx4 v[162:165], v[246:247], off offset:64
	v_lshlrev_b64 v[246:247], 6, v[250:251]
	v_lshl_add_u64 v[246:247], s[58:59], 0, v[246:247]
	v_lshl_add_u64 v[246:247], v[246:247], 0, s[20:21]
	global_load_dword v147, v[246:247], off
	s_waitcnt vmcnt(5)
	v_permlane16_swap_b32_e32 v130, v132
	v_permlane16_swap_b32_e32 v131, v133
	v_permlane16_swap_b32_e32 v134, v136
	v_permlane16_swap_b32_e32 v135, v137
	v_permlane16_swap_b32_e32 v138, v140
	v_permlane16_swap_b32_e32 v139, v141
	v_permlane16_swap_b32_e32 v142, v144
	v_permlane16_swap_b32_e32 v143, v145
	v_lshlrev_b32_e32 v228, 16, v130
	v_and_b32_e32 v229, 0xffff0000, v130
	v_lshlrev_b32_e32 v230, 16, v131
	v_and_b32_e32 v231, 0xffff0000, v131
	v_lshlrev_b32_e32 v232, 16, v132
	v_and_b32_e32 v233, 0xffff0000, v132
	v_lshlrev_b32_e32 v234, 16, v133
	v_and_b32_e32 v235, 0xffff0000, v133
	v_lshlrev_b32_e32 v236, 16, v134
	v_and_b32_e32 v237, 0xffff0000, v134
	v_lshlrev_b32_e32 v238, 16, v135
	v_and_b32_e32 v239, 0xffff0000, v135
	v_lshlrev_b32_e32 v240, 16, v136
	v_and_b32_e32 v241, 0xffff0000, v136
	v_lshlrev_b32_e32 v242, 16, v137
	v_and_b32_e32 v243, 0xffff0000, v137
	v_add_f32_e32 v250, v228, v229
	v_add_f32_e32 v251, v230, v231
	v_add_f32_e32 v250, v250, v232
	v_add_f32_e32 v251, v251, v233
	v_add_f32_e32 v250, v250, v234
	v_add_f32_e32 v251, v251, v235
	v_add_f32_e32 v250, v250, v236
	v_add_f32_e32 v251, v251, v237
	v_add_f32_e32 v250, v250, v238
	v_add_f32_e32 v251, v251, v239
	v_add_f32_e32 v250, v250, v240
	v_add_f32_e32 v251, v251, v241
	v_add_f32_e32 v250, v250, v242
	v_add_f32_e32 v251, v251, v243
	v_add_f32_e32 v250, v250, v251
	v_mov_b32_e32 v251, v250
	s_nop 1
	v_permlane16_swap_b32_e32 v251, v250
	v_add_f32_e32 v250, v250, v251
	v_mov_b32_e32 v251, v250
	s_nop 1
	v_permlane32_swap_b32_e32 v251, v250
	v_add_f32_e32 v250, v250, v251
	v_fmac_f32_e32 v228, 0xbc800000, v250
	v_fmac_f32_e32 v229, 0xbc800000, v250
	v_fmac_f32_e32 v230, 0xbc800000, v250
	v_fmac_f32_e32 v231, 0xbc800000, v250
	v_fmac_f32_e32 v232, 0xbc800000, v250
	v_fmac_f32_e32 v233, 0xbc800000, v250
	v_fmac_f32_e32 v234, 0xbc800000, v250
	v_fmac_f32_e32 v235, 0xbc800000, v250
	v_fmac_f32_e32 v236, 0xbc800000, v250
	v_fmac_f32_e32 v237, 0xbc800000, v250
	v_fmac_f32_e32 v238, 0xbc800000, v250
	v_fmac_f32_e32 v239, 0xbc800000, v250
	v_fmac_f32_e32 v240, 0xbc800000, v250
	v_fmac_f32_e32 v241, 0xbc800000, v250
	v_fmac_f32_e32 v242, 0xbc800000, v250
	v_fmac_f32_e32 v243, 0xbc800000, v250
	v_mul_f32_e32 v250, v228, v228
	v_mul_f32_e32 v251, v229, v229
	v_fmac_f32_e32 v250, v230, v230
	v_fmac_f32_e32 v251, v231, v231
	v_fmac_f32_e32 v250, v232, v232
	v_fmac_f32_e32 v251, v233, v233
	v_fmac_f32_e32 v250, v234, v234
	v_fmac_f32_e32 v251, v235, v235
	v_fmac_f32_e32 v250, v236, v236
	v_fmac_f32_e32 v251, v237, v237
	v_fmac_f32_e32 v250, v238, v238
	v_fmac_f32_e32 v251, v239, v239
	v_fmac_f32_e32 v250, v240, v240
	v_fmac_f32_e32 v251, v241, v241
	v_fmac_f32_e32 v250, v242, v242
	v_fmac_f32_e32 v251, v243, v243
	v_add_f32_e32 v250, v250, v251
	v_mov_b32_e32 v251, v250
	s_nop 1
	v_permlane16_swap_b32_e32 v251, v250
	v_add_f32_e32 v250, v250, v251
	v_mov_b32_e32 v251, v250
	s_nop 1
	v_permlane32_swap_b32_e32 v251, v250
	v_add_f32_e32 v250, v250, v251
	v_fmamk_f32 v250, v250, 0x3c800000, v166
	v_mul_f32_e32 v251, 0x4b800000, v250
	v_cmp_gt_f32_e64 s[0:1], s16, v250
	s_nop 1
	v_cndmask_b32_e64 v250, v250, v251, s[0:1]
	v_rsq_f32_e32 v252, v250
	s_nop 0
	v_mul_f32_e32 v251, 0x45800000, v252
	v_cndmask_b32_e64 v252, v252, v251, s[0:1]
	v_mul_f32_e32 v228, v228, v252
	v_fma_f32 v228, v228, v194, v210
	v_lshlrev_b32_e32 v244, 16, v138
	v_fmac_f32_e32 v228, v146, v244
	v_mul_f32_e32 v228, v126, v228
	v_mul_f32_e32 v229, v229, v252
	v_fma_f32 v229, v229, v195, v211
	v_and_b32_e32 v244, 0xffff0000, v138
	v_fmac_f32_e32 v229, v146, v244
	v_mul_f32_e32 v229, v127, v229
	v_mul_f32_e32 v230, v230, v252
	v_fma_f32 v230, v230, v196, v212
	v_lshlrev_b32_e32 v244, 16, v139
	v_fmac_f32_e32 v230, v146, v244
	v_mul_f32_e32 v230, v128, v230
	v_mul_f32_e32 v231, v231, v252
	v_fma_f32 v231, v231, v197, v213
	v_and_b32_e32 v244, 0xffff0000, v139
	v_fmac_f32_e32 v231, v146, v244
	v_mul_f32_e32 v231, v129, v231
	v_mul_f32_e32 v232, v232, v252
	v_fma_f32 v232, v232, v198, v214
	v_lshlrev_b32_e32 v244, 16, v140
	v_fmac_f32_e32 v232, v146, v244
	v_mul_f32_e32 v232, v122, v232
	v_mul_f32_e32 v233, v233, v252
	v_fma_f32 v233, v233, v199, v215
	v_and_b32_e32 v244, 0xffff0000, v140
	v_fmac_f32_e32 v233, v146, v244
	v_mul_f32_e32 v233, v123, v233
	v_mul_f32_e32 v234, v234, v252
	v_fma_f32 v234, v234, v200, v216
	v_lshlrev_b32_e32 v244, 16, v141
	v_fmac_f32_e32 v234, v146, v244
	v_mul_f32_e32 v234, v124, v234
	v_mul_f32_e32 v235, v235, v252
	v_fma_f32 v235, v235, v201, v217
	v_and_b32_e32 v244, 0xffff0000, v141
	v_fmac_f32_e32 v235, v146, v244
	v_mul_f32_e32 v235, v125, v235
	v_mul_f32_e32 v236, v236, v252
	v_fma_f32 v236, v236, v202, v218
	v_lshlrev_b32_e32 v244, 16, v142
	v_fmac_f32_e32 v236, v146, v244
	v_mul_f32_e32 v236, v118, v236
	v_mul_f32_e32 v237, v237, v252
	v_fma_f32 v237, v237, v203, v219
	v_and_b32_e32 v244, 0xffff0000, v142
	v_fmac_f32_e32 v237, v146, v244
	v_mul_f32_e32 v237, v119, v237
	v_mul_f32_e32 v238, v238, v252
	v_fma_f32 v238, v238, v204, v220
	v_lshlrev_b32_e32 v244, 16, v143
	v_fmac_f32_e32 v238, v146, v244
	v_mul_f32_e32 v238, v120, v238
	v_mul_f32_e32 v239, v239, v252
	v_fma_f32 v239, v239, v205, v221
	v_and_b32_e32 v244, 0xffff0000, v143
	v_fmac_f32_e32 v239, v146, v244
	v_mul_f32_e32 v239, v121, v239
	v_mul_f32_e32 v240, v240, v252
	v_fma_f32 v240, v240, v206, v222
	v_lshlrev_b32_e32 v244, 16, v144
	v_fmac_f32_e32 v240, v146, v244
	v_mul_f32_e32 v240, v114, v240
	v_mul_f32_e32 v241, v241, v252
	v_fma_f32 v241, v241, v207, v223
	v_and_b32_e32 v244, 0xffff0000, v144
	v_fmac_f32_e32 v241, v146, v244
	v_mul_f32_e32 v241, v115, v241
	v_mul_f32_e32 v242, v242, v252
	v_fma_f32 v242, v242, v208, v224
	v_lshlrev_b32_e32 v244, 16, v145
	v_fmac_f32_e32 v242, v146, v244
	v_mul_f32_e32 v242, v116, v242
	v_mul_f32_e32 v243, v243, v252
	v_fma_f32 v243, v243, v209, v225
	v_and_b32_e32 v244, 0xffff0000, v145
	v_fmac_f32_e32 v243, v146, v244
	v_mul_f32_e32 v243, v117, v243
	v_cvt_pk_bf16_f32 v228, v228, v229
	v_cvt_pk_bf16_f32 v229, v230, v231
	v_cvt_pk_bf16_f32 v230, v232, v233
	v_cvt_pk_bf16_f32 v231, v234, v235
	v_cvt_pk_bf16_f32 v232, v236, v237
	v_cvt_pk_bf16_f32 v233, v238, v239
	v_cvt_pk_bf16_f32 v234, v240, v241
	v_cvt_pk_bf16_f32 v235, v242, v243
	s_nop 1
	v_permlane16_swap_b32_e32 v228, v230
	v_permlane16_swap_b32_e32 v229, v231
	v_permlane16_swap_b32_e32 v232, v234
	v_permlane16_swap_b32_e32 v233, v235
	v_mov_b64_e32 v[248:249], v[148:149]
	s_add_i32 s0, s19, 32
	v_add_u32_e32 v253, s0, v0
	v_cmp_gt_i32_e32 vcc, s14, v253
	s_nop 1
	v_cndmask_b32_e32 v253, v168, v253, vcc
	v_mov_b64_e32 v[148:149], s[88:89]
	v_mad_i64_i32 v[148:149], s[0:1], v253, s15, v[148:149]
	v_mov_b32_e32 v244, v254
	v_mov_b32_e32 v245, 0
	v_lshl_add_u64 v[148:149], v[148:149], 0, v[244:245]
	global_load_dwordx4 v[130:133], v[148:149], off offset:0
	global_load_dwordx4 v[134:137], v[148:149], off offset:64
	v_ashrrev_i32_e32 v251, 31, v253
	v_mov_b32_e32 v250, v253
	v_lshlrev_b64 v[246:247], 11, v[250:251]
	v_lshl_add_u64 v[246:247], s[54:55], 0, v[246:247]
	v_lshl_add_u64 v[246:247], v[246:247], 0, v[244:245]
	global_load_dwordx4 v[138:141], v[246:247], off offset:0
	global_load_dwordx4 v[142:145], v[246:247], off offset:64
	v_lshlrev_b64 v[246:247], 6, v[250:251]
	v_lshl_add_u64 v[246:247], s[58:59], 0, v[246:247]
	v_lshl_add_u64 v[246:247], v[246:247], 0, s[20:21]
	global_load_dword v146, v[246:247], off
	s_add_i32 s0, s19, 0
	v_add_u32_e32 v253, s0, v0
	v_cmp_gt_i32_e32 vcc, s14, v253
	s_and_saveexec_b64 s[0:1], vcc
	global_store_dwordx4 v[248:249], v[228:231], off offset:0
	global_store_dwordx4 v[248:249], v[232:235], off offset:64
	s_or_b64 exec, exec, s[0:1]
	s_waitcnt vmcnt(5)
	v_permlane16_swap_b32_e32 v150, v152
	v_permlane16_swap_b32_e32 v151, v153
	v_permlane16_swap_b32_e32 v154, v156
	v_permlane16_swap_b32_e32 v155, v157
	v_permlane16_swap_b32_e32 v158, v160
	v_permlane16_swap_b32_e32 v159, v161
	v_permlane16_swap_b32_e32 v162, v164
	v_permlane16_swap_b32_e32 v163, v165
	v_lshlrev_b32_e32 v228, 16, v150
	v_and_b32_e32 v229, 0xffff0000, v150
	v_lshlrev_b32_e32 v230, 16, v151
	v_and_b32_e32 v231, 0xffff0000, v151
	v_lshlrev_b32_e32 v232, 16, v152
	v_and_b32_e32 v233, 0xffff0000, v152
	v_lshlrev_b32_e32 v234, 16, v153
	v_and_b32_e32 v235, 0xffff0000, v153
	v_lshlrev_b32_e32 v236, 16, v154
	v_and_b32_e32 v237, 0xffff0000, v154
	v_lshlrev_b32_e32 v238, 16, v155
	v_and_b32_e32 v239, 0xffff0000, v155
	v_lshlrev_b32_e32 v240, 16, v156
	v_and_b32_e32 v241, 0xffff0000, v156
	v_lshlrev_b32_e32 v242, 16, v157
	v_and_b32_e32 v243, 0xffff0000, v157
	v_add_f32_e32 v250, v228, v229
	v_add_f32_e32 v251, v230, v231
	v_add_f32_e32 v250, v250, v232
	v_add_f32_e32 v251, v251, v233
	v_add_f32_e32 v250, v250, v234
	v_add_f32_e32 v251, v251, v235
	v_add_f32_e32 v250, v250, v236
	v_add_f32_e32 v251, v251, v237
	v_add_f32_e32 v250, v250, v238
	v_add_f32_e32 v251, v251, v239
	v_add_f32_e32 v250, v250, v240
	v_add_f32_e32 v251, v251, v241
	v_add_f32_e32 v250, v250, v242
	v_add_f32_e32 v251, v251, v243
	v_add_f32_e32 v250, v250, v251
	v_mov_b32_e32 v251, v250
	s_nop 1
	v_permlane16_swap_b32_e32 v251, v250
	v_add_f32_e32 v250, v250, v251
	v_mov_b32_e32 v251, v250
	s_nop 1
	v_permlane32_swap_b32_e32 v251, v250
	v_add_f32_e32 v250, v250, v251
	v_fmac_f32_e32 v228, 0xbc800000, v250
	v_fmac_f32_e32 v229, 0xbc800000, v250
	v_fmac_f32_e32 v230, 0xbc800000, v250
	v_fmac_f32_e32 v231, 0xbc800000, v250
	v_fmac_f32_e32 v232, 0xbc800000, v250
	v_fmac_f32_e32 v233, 0xbc800000, v250
	v_fmac_f32_e32 v234, 0xbc800000, v250
	v_fmac_f32_e32 v235, 0xbc800000, v250
	v_fmac_f32_e32 v236, 0xbc800000, v250
	v_fmac_f32_e32 v237, 0xbc800000, v250
	v_fmac_f32_e32 v238, 0xbc800000, v250
	v_fmac_f32_e32 v239, 0xbc800000, v250
	v_fmac_f32_e32 v240, 0xbc800000, v250
	v_fmac_f32_e32 v241, 0xbc800000, v250
	v_fmac_f32_e32 v242, 0xbc800000, v250
	v_fmac_f32_e32 v243, 0xbc800000, v250
	v_mul_f32_e32 v250, v228, v228
	v_mul_f32_e32 v251, v229, v229
	v_fmac_f32_e32 v250, v230, v230
	v_fmac_f32_e32 v251, v231, v231
	v_fmac_f32_e32 v250, v232, v232
	v_fmac_f32_e32 v251, v233, v233
	v_fmac_f32_e32 v250, v234, v234
	v_fmac_f32_e32 v251, v235, v235
	v_fmac_f32_e32 v250, v236, v236
	v_fmac_f32_e32 v251, v237, v237
	v_fmac_f32_e32 v250, v238, v238
	v_fmac_f32_e32 v251, v239, v239
	v_fmac_f32_e32 v250, v240, v240
	v_fmac_f32_e32 v251, v241, v241
	v_fmac_f32_e32 v250, v242, v242
	v_fmac_f32_e32 v251, v243, v243
	v_add_f32_e32 v250, v250, v251
	v_mov_b32_e32 v251, v250
	s_nop 1
	v_permlane16_swap_b32_e32 v251, v250
	v_add_f32_e32 v250, v250, v251
	v_mov_b32_e32 v251, v250
	s_nop 1
	v_permlane32_swap_b32_e32 v251, v250
	v_add_f32_e32 v250, v250, v251
	v_fmamk_f32 v250, v250, 0x3c800000, v166
	v_mul_f32_e32 v251, 0x4b800000, v250
	v_cmp_gt_f32_e64 s[0:1], s16, v250
	s_nop 1
	v_cndmask_b32_e64 v250, v250, v251, s[0:1]
	v_rsq_f32_e32 v252, v250
	s_nop 0
	v_mul_f32_e32 v251, 0x45800000, v252
	v_cndmask_b32_e64 v252, v252, v251, s[0:1]
	v_mul_f32_e32 v228, v228, v252
	v_fma_f32 v228, v228, v194, v210
	v_lshlrev_b32_e32 v244, 16, v158
	v_fmac_f32_e32 v228, v147, v244
	v_mul_f32_e32 v228, v110, v228
	v_mul_f32_e32 v229, v229, v252
	v_fma_f32 v229, v229, v195, v211
	v_and_b32_e32 v244, 0xffff0000, v158
	v_fmac_f32_e32 v229, v147, v244
	v_mul_f32_e32 v229, v111, v229
	v_mul_f32_e32 v230, v230, v252
	v_fma_f32 v230, v230, v196, v212
	v_lshlrev_b32_e32 v244, 16, v159
	v_fmac_f32_e32 v230, v147, v244
	v_mul_f32_e32 v230, v112, v230
	v_mul_f32_e32 v231, v231, v252
	v_fma_f32 v231, v231, v197, v213
	v_and_b32_e32 v244, 0xffff0000, v159
	v_fmac_f32_e32 v231, v147, v244
	v_mul_f32_e32 v231, v113, v231
	v_mul_f32_e32 v232, v232, v252
	v_fma_f32 v232, v232, v198, v214
	v_lshlrev_b32_e32 v244, 16, v160
	v_fmac_f32_e32 v232, v147, v244
	v_mul_f32_e32 v232, v106, v232
	v_mul_f32_e32 v233, v233, v252
	v_fma_f32 v233, v233, v199, v215
	v_and_b32_e32 v244, 0xffff0000, v160
	v_fmac_f32_e32 v233, v147, v244
	v_mul_f32_e32 v233, v107, v233
	v_mul_f32_e32 v234, v234, v252
	v_fma_f32 v234, v234, v200, v216
	v_lshlrev_b32_e32 v244, 16, v161
	v_fmac_f32_e32 v234, v147, v244
	v_mul_f32_e32 v234, v108, v234
	v_mul_f32_e32 v235, v235, v252
	v_fma_f32 v235, v235, v201, v217
	v_and_b32_e32 v244, 0xffff0000, v161
	v_fmac_f32_e32 v235, v147, v244
	v_mul_f32_e32 v235, v109, v235
	v_mul_f32_e32 v236, v236, v252
	v_fma_f32 v236, v236, v202, v218
	v_lshlrev_b32_e32 v244, 16, v162
	v_fmac_f32_e32 v236, v147, v244
	v_mul_f32_e32 v236, v102, v236
	v_mul_f32_e32 v237, v237, v252
	v_fma_f32 v237, v237, v203, v219
	v_and_b32_e32 v244, 0xffff0000, v162
	v_fmac_f32_e32 v237, v147, v244
	v_mul_f32_e32 v237, v103, v237
	v_mul_f32_e32 v238, v238, v252
	v_fma_f32 v238, v238, v204, v220
	v_lshlrev_b32_e32 v244, 16, v163
	v_fmac_f32_e32 v238, v147, v244
	v_mul_f32_e32 v238, v104, v238
	v_mul_f32_e32 v239, v239, v252
	v_fma_f32 v239, v239, v205, v221
	v_and_b32_e32 v244, 0xffff0000, v163
	v_fmac_f32_e32 v239, v147, v244
	v_mul_f32_e32 v239, v105, v239
	v_mul_f32_e32 v240, v240, v252
	v_fma_f32 v240, v240, v206, v222
	v_lshlrev_b32_e32 v244, 16, v164
	v_fmac_f32_e32 v240, v147, v244
	v_mul_f32_e32 v240, v98, v240
	v_mul_f32_e32 v241, v241, v252
	v_fma_f32 v241, v241, v207, v223
	v_and_b32_e32 v244, 0xffff0000, v164
	v_fmac_f32_e32 v241, v147, v244
	v_mul_f32_e32 v241, v99, v241
	v_mul_f32_e32 v242, v242, v252
	v_fma_f32 v242, v242, v208, v224
	v_lshlrev_b32_e32 v244, 16, v165
	v_fmac_f32_e32 v242, v147, v244
	v_mul_f32_e32 v242, v100, v242
	v_mul_f32_e32 v243, v243, v252
	v_fma_f32 v243, v243, v209, v225
	v_and_b32_e32 v244, 0xffff0000, v165
	v_fmac_f32_e32 v243, v147, v244
	v_mul_f32_e32 v243, v101, v243
	v_cvt_pk_bf16_f32 v228, v228, v229
	v_cvt_pk_bf16_f32 v229, v230, v231
	v_cvt_pk_bf16_f32 v230, v232, v233
	v_cvt_pk_bf16_f32 v231, v234, v235
	v_cvt_pk_bf16_f32 v232, v236, v237
	v_cvt_pk_bf16_f32 v233, v238, v239
	v_cvt_pk_bf16_f32 v234, v240, v241
	v_cvt_pk_bf16_f32 v235, v242, v243
	s_nop 1
	v_permlane16_swap_b32_e32 v228, v230
	v_permlane16_swap_b32_e32 v229, v231
	v_permlane16_swap_b32_e32 v232, v234
	v_permlane16_swap_b32_e32 v233, v235
	v_mov_b64_e32 v[248:249], v[226:227]
	s_add_i32 s0, s19, 48
	v_add_u32_e32 v253, s0, v0
	v_cmp_gt_i32_e32 vcc, s14, v253
	s_nop 1
	v_cndmask_b32_e32 v253, v168, v253, vcc
	v_mov_b64_e32 v[226:227], s[88:89]
	v_mad_i64_i32 v[226:227], s[0:1], v253, s15, v[226:227]
	v_mov_b32_e32 v244, v254
	v_mov_b32_e32 v245, 0
	v_lshl_add_u64 v[226:227], v[226:227], 0, v[244:245]
	global_load_dwordx4 v[150:153], v[226:227], off offset:0
	global_load_dwordx4 v[154:157], v[226:227], off offset:64
	v_ashrrev_i32_e32 v251, 31, v253
	v_mov_b32_e32 v250, v253
	v_lshlrev_b64 v[246:247], 11, v[250:251]
	v_lshl_add_u64 v[246:247], s[54:55], 0, v[246:247]
	v_lshl_add_u64 v[246:247], v[246:247], 0, v[244:245]
	global_load_dwordx4 v[158:161], v[246:247], off offset:0
	global_load_dwordx4 v[162:165], v[246:247], off offset:64
	v_lshlrev_b64 v[246:247], 6, v[250:251]
	v_lshl_add_u64 v[246:247], s[58:59], 0, v[246:247]
	v_lshl_add_u64 v[246:247], v[246:247], 0, s[20:21]
	global_load_dword v147, v[246:247], off
	s_add_i32 s0, s19, 16
	v_add_u32_e32 v253, s0, v0
	v_cmp_gt_i32_e32 vcc, s14, v253
	s_and_saveexec_b64 s[0:1], vcc
	global_store_dwordx4 v[248:249], v[228:231], off offset:0
	global_store_dwordx4 v[248:249], v[232:235], off offset:64
	s_or_b64 exec, exec, s[0:1]
	s_waitcnt vmcnt(5)
	v_permlane16_swap_b32_e32 v130, v132
	v_permlane16_swap_b32_e32 v131, v133
	v_permlane16_swap_b32_e32 v134, v136
	v_permlane16_swap_b32_e32 v135, v137
	v_permlane16_swap_b32_e32 v138, v140
	v_permlane16_swap_b32_e32 v139, v141
	v_permlane16_swap_b32_e32 v142, v144
	v_permlane16_swap_b32_e32 v143, v145
	v_lshlrev_b32_e32 v228, 16, v130
	v_and_b32_e32 v229, 0xffff0000, v130
	v_lshlrev_b32_e32 v230, 16, v131
	v_and_b32_e32 v231, 0xffff0000, v131
	v_lshlrev_b32_e32 v232, 16, v132
	v_and_b32_e32 v233, 0xffff0000, v132
	v_lshlrev_b32_e32 v234, 16, v133
	v_and_b32_e32 v235, 0xffff0000, v133
	v_lshlrev_b32_e32 v236, 16, v134
	v_and_b32_e32 v237, 0xffff0000, v134
	v_lshlrev_b32_e32 v238, 16, v135
	v_and_b32_e32 v239, 0xffff0000, v135
	v_lshlrev_b32_e32 v240, 16, v136
	v_and_b32_e32 v241, 0xffff0000, v136
	v_lshlrev_b32_e32 v242, 16, v137
	v_and_b32_e32 v243, 0xffff0000, v137
	v_add_f32_e32 v250, v228, v229
	v_add_f32_e32 v251, v230, v231
	v_add_f32_e32 v250, v250, v232
	v_add_f32_e32 v251, v251, v233
	v_add_f32_e32 v250, v250, v234
	v_add_f32_e32 v251, v251, v235
	v_add_f32_e32 v250, v250, v236
	v_add_f32_e32 v251, v251, v237
	v_add_f32_e32 v250, v250, v238
	v_add_f32_e32 v251, v251, v239
	v_add_f32_e32 v250, v250, v240
	v_add_f32_e32 v251, v251, v241
	v_add_f32_e32 v250, v250, v242
	v_add_f32_e32 v251, v251, v243
	v_add_f32_e32 v250, v250, v251
	v_mov_b32_e32 v251, v250
	s_nop 1
	v_permlane16_swap_b32_e32 v251, v250
	v_add_f32_e32 v250, v250, v251
	v_mov_b32_e32 v251, v250
	s_nop 1
	v_permlane32_swap_b32_e32 v251, v250
	v_add_f32_e32 v250, v250, v251
	v_fmac_f32_e32 v228, 0xbc800000, v250
	v_fmac_f32_e32 v229, 0xbc800000, v250
	v_fmac_f32_e32 v230, 0xbc800000, v250
	v_fmac_f32_e32 v231, 0xbc800000, v250
	v_fmac_f32_e32 v232, 0xbc800000, v250
	v_fmac_f32_e32 v233, 0xbc800000, v250
	v_fmac_f32_e32 v234, 0xbc800000, v250
	v_fmac_f32_e32 v235, 0xbc800000, v250
	v_fmac_f32_e32 v236, 0xbc800000, v250
	v_fmac_f32_e32 v237, 0xbc800000, v250
	v_fmac_f32_e32 v238, 0xbc800000, v250
	v_fmac_f32_e32 v239, 0xbc800000, v250
	v_fmac_f32_e32 v240, 0xbc800000, v250
	v_fmac_f32_e32 v241, 0xbc800000, v250
	v_fmac_f32_e32 v242, 0xbc800000, v250
	v_fmac_f32_e32 v243, 0xbc800000, v250
	v_mul_f32_e32 v250, v228, v228
	v_mul_f32_e32 v251, v229, v229
	v_fmac_f32_e32 v250, v230, v230
	v_fmac_f32_e32 v251, v231, v231
	v_fmac_f32_e32 v250, v232, v232
	v_fmac_f32_e32 v251, v233, v233
	v_fmac_f32_e32 v250, v234, v234
	v_fmac_f32_e32 v251, v235, v235
	v_fmac_f32_e32 v250, v236, v236
	v_fmac_f32_e32 v251, v237, v237
	v_fmac_f32_e32 v250, v238, v238
	v_fmac_f32_e32 v251, v239, v239
	v_fmac_f32_e32 v250, v240, v240
	v_fmac_f32_e32 v251, v241, v241
	v_fmac_f32_e32 v250, v242, v242
	v_fmac_f32_e32 v251, v243, v243
	v_add_f32_e32 v250, v250, v251
	v_mov_b32_e32 v251, v250
	s_nop 1
	v_permlane16_swap_b32_e32 v251, v250
	v_add_f32_e32 v250, v250, v251
	v_mov_b32_e32 v251, v250
	s_nop 1
	v_permlane32_swap_b32_e32 v251, v250
	v_add_f32_e32 v250, v250, v251
	v_fmamk_f32 v250, v250, 0x3c800000, v166
	v_mul_f32_e32 v251, 0x4b800000, v250
	v_cmp_gt_f32_e64 s[0:1], s16, v250
	s_nop 1
	v_cndmask_b32_e64 v250, v250, v251, s[0:1]
	v_rsq_f32_e32 v252, v250
	s_nop 0
	v_mul_f32_e32 v251, 0x45800000, v252
	v_cndmask_b32_e64 v252, v252, v251, s[0:1]
	v_mul_f32_e32 v228, v228, v252
	v_fma_f32 v228, v228, v194, v210
	v_lshlrev_b32_e32 v244, 16, v138
	v_fmac_f32_e32 v228, v146, v244
	v_mul_f32_e32 v228, v94, v228
	v_mul_f32_e32 v229, v229, v252
	v_fma_f32 v229, v229, v195, v211
	v_and_b32_e32 v244, 0xffff0000, v138
	v_fmac_f32_e32 v229, v146, v244
	v_mul_f32_e32 v229, v95, v229
	v_mul_f32_e32 v230, v230, v252
	v_fma_f32 v230, v230, v196, v212
	v_lshlrev_b32_e32 v244, 16, v139
	v_fmac_f32_e32 v230, v146, v244
	v_mul_f32_e32 v230, v96, v230
	v_mul_f32_e32 v231, v231, v252
	v_fma_f32 v231, v231, v197, v213
	v_and_b32_e32 v244, 0xffff0000, v139
	v_fmac_f32_e32 v231, v146, v244
	v_mul_f32_e32 v231, v97, v231
	v_mul_f32_e32 v232, v232, v252
	v_fma_f32 v232, v232, v198, v214
	v_lshlrev_b32_e32 v244, 16, v140
	v_fmac_f32_e32 v232, v146, v244
	v_mul_f32_e32 v232, v90, v232
	v_mul_f32_e32 v233, v233, v252
	v_fma_f32 v233, v233, v199, v215
	v_and_b32_e32 v244, 0xffff0000, v140
	v_fmac_f32_e32 v233, v146, v244
	v_mul_f32_e32 v233, v91, v233
	v_mul_f32_e32 v234, v234, v252
	v_fma_f32 v234, v234, v200, v216
	v_lshlrev_b32_e32 v244, 16, v141
	v_fmac_f32_e32 v234, v146, v244
	v_mul_f32_e32 v234, v92, v234
	v_mul_f32_e32 v235, v235, v252
	v_fma_f32 v235, v235, v201, v217
	v_and_b32_e32 v244, 0xffff0000, v141
	v_fmac_f32_e32 v235, v146, v244
	v_mul_f32_e32 v235, v93, v235
	v_mul_f32_e32 v236, v236, v252
	v_fma_f32 v236, v236, v202, v218
	v_lshlrev_b32_e32 v244, 16, v142
	v_fmac_f32_e32 v236, v146, v244
	v_mul_f32_e32 v236, v86, v236
	v_mul_f32_e32 v237, v237, v252
	v_fma_f32 v237, v237, v203, v219
	v_and_b32_e32 v244, 0xffff0000, v142
	v_fmac_f32_e32 v237, v146, v244
	v_mul_f32_e32 v237, v87, v237
	v_mul_f32_e32 v238, v238, v252
	v_fma_f32 v238, v238, v204, v220
	v_lshlrev_b32_e32 v244, 16, v143
	v_fmac_f32_e32 v238, v146, v244
	v_mul_f32_e32 v238, v88, v238
	v_mul_f32_e32 v239, v239, v252
	v_fma_f32 v239, v239, v205, v221
	v_and_b32_e32 v244, 0xffff0000, v143
	v_fmac_f32_e32 v239, v146, v244
	v_mul_f32_e32 v239, v89, v239
	v_mul_f32_e32 v240, v240, v252
	v_fma_f32 v240, v240, v206, v222
	v_lshlrev_b32_e32 v244, 16, v144
	v_fmac_f32_e32 v240, v146, v244
	v_mul_f32_e32 v240, v82, v240
	v_mul_f32_e32 v241, v241, v252
	v_fma_f32 v241, v241, v207, v223
	v_and_b32_e32 v244, 0xffff0000, v144
	v_fmac_f32_e32 v241, v146, v244
	v_mul_f32_e32 v241, v83, v241
	v_mul_f32_e32 v242, v242, v252
	v_fma_f32 v242, v242, v208, v224
	v_lshlrev_b32_e32 v244, 16, v145
	v_fmac_f32_e32 v242, v146, v244
	v_mul_f32_e32 v242, v84, v242
	v_mul_f32_e32 v243, v243, v252
	v_fma_f32 v243, v243, v209, v225
	v_and_b32_e32 v244, 0xffff0000, v145
	v_fmac_f32_e32 v243, v146, v244
	v_mul_f32_e32 v243, v85, v243
	v_cvt_pk_bf16_f32 v228, v228, v229
	v_cvt_pk_bf16_f32 v229, v230, v231
	v_cvt_pk_bf16_f32 v230, v232, v233
	v_cvt_pk_bf16_f32 v231, v234, v235
	v_cvt_pk_bf16_f32 v232, v236, v237
	v_cvt_pk_bf16_f32 v233, v238, v239
	v_cvt_pk_bf16_f32 v234, v240, v241
	v_cvt_pk_bf16_f32 v235, v242, v243
	s_nop 1
	v_permlane16_swap_b32_e32 v228, v230
	v_permlane16_swap_b32_e32 v229, v231
	v_permlane16_swap_b32_e32 v232, v234
	v_permlane16_swap_b32_e32 v233, v235
	v_mov_b64_e32 v[248:249], v[148:149]
	s_add_i32 s0, s19, 64
	v_add_u32_e32 v253, s0, v0
	v_cmp_gt_i32_e32 vcc, s14, v253
	s_nop 1
	v_cndmask_b32_e32 v253, v168, v253, vcc
	v_mov_b64_e32 v[148:149], s[88:89]
	v_mad_i64_i32 v[148:149], s[0:1], v253, s15, v[148:149]
	v_mov_b32_e32 v244, v254
	v_mov_b32_e32 v245, 0
	v_lshl_add_u64 v[148:149], v[148:149], 0, v[244:245]
	global_load_dwordx4 v[130:133], v[148:149], off offset:0
	global_load_dwordx4 v[134:137], v[148:149], off offset:64
	v_ashrrev_i32_e32 v251, 31, v253
	v_mov_b32_e32 v250, v253
	v_lshlrev_b64 v[246:247], 11, v[250:251]
	v_lshl_add_u64 v[246:247], s[54:55], 0, v[246:247]
	v_lshl_add_u64 v[246:247], v[246:247], 0, v[244:245]
	global_load_dwordx4 v[138:141], v[246:247], off offset:0
	global_load_dwordx4 v[142:145], v[246:247], off offset:64
	v_lshlrev_b64 v[246:247], 6, v[250:251]
	v_lshl_add_u64 v[246:247], s[58:59], 0, v[246:247]
	v_lshl_add_u64 v[246:247], v[246:247], 0, s[20:21]
	global_load_dword v146, v[246:247], off
	s_add_i32 s0, s19, 32
	v_add_u32_e32 v253, s0, v0
	v_cmp_gt_i32_e32 vcc, s14, v253
	s_and_saveexec_b64 s[0:1], vcc
	global_store_dwordx4 v[248:249], v[228:231], off offset:0
	global_store_dwordx4 v[248:249], v[232:235], off offset:64
	s_or_b64 exec, exec, s[0:1]
	s_waitcnt vmcnt(5)
	v_permlane16_swap_b32_e32 v150, v152
	v_permlane16_swap_b32_e32 v151, v153
	v_permlane16_swap_b32_e32 v154, v156
	v_permlane16_swap_b32_e32 v155, v157
	v_permlane16_swap_b32_e32 v158, v160
	v_permlane16_swap_b32_e32 v159, v161
	v_permlane16_swap_b32_e32 v162, v164
	v_permlane16_swap_b32_e32 v163, v165
	v_lshlrev_b32_e32 v228, 16, v150
	v_and_b32_e32 v229, 0xffff0000, v150
	v_lshlrev_b32_e32 v230, 16, v151
	v_and_b32_e32 v231, 0xffff0000, v151
	v_lshlrev_b32_e32 v232, 16, v152
	v_and_b32_e32 v233, 0xffff0000, v152
	v_lshlrev_b32_e32 v234, 16, v153
	v_and_b32_e32 v235, 0xffff0000, v153
	v_lshlrev_b32_e32 v236, 16, v154
	v_and_b32_e32 v237, 0xffff0000, v154
	v_lshlrev_b32_e32 v238, 16, v155
	v_and_b32_e32 v239, 0xffff0000, v155
	v_lshlrev_b32_e32 v240, 16, v156
	v_and_b32_e32 v241, 0xffff0000, v156
	v_lshlrev_b32_e32 v242, 16, v157
	v_and_b32_e32 v243, 0xffff0000, v157
	v_add_f32_e32 v250, v228, v229
	v_add_f32_e32 v251, v230, v231
	v_add_f32_e32 v250, v250, v232
	v_add_f32_e32 v251, v251, v233
	v_add_f32_e32 v250, v250, v234
	v_add_f32_e32 v251, v251, v235
	v_add_f32_e32 v250, v250, v236
	v_add_f32_e32 v251, v251, v237
	v_add_f32_e32 v250, v250, v238
	v_add_f32_e32 v251, v251, v239
	v_add_f32_e32 v250, v250, v240
	v_add_f32_e32 v251, v251, v241
	v_add_f32_e32 v250, v250, v242
	v_add_f32_e32 v251, v251, v243
	v_add_f32_e32 v250, v250, v251
	v_mov_b32_e32 v251, v250
	s_nop 1
	v_permlane16_swap_b32_e32 v251, v250
	v_add_f32_e32 v250, v250, v251
	v_mov_b32_e32 v251, v250
	s_nop 1
	v_permlane32_swap_b32_e32 v251, v250
	v_add_f32_e32 v250, v250, v251
	v_fmac_f32_e32 v228, 0xbc800000, v250
	v_fmac_f32_e32 v229, 0xbc800000, v250
	v_fmac_f32_e32 v230, 0xbc800000, v250
	v_fmac_f32_e32 v231, 0xbc800000, v250
	v_fmac_f32_e32 v232, 0xbc800000, v250
	v_fmac_f32_e32 v233, 0xbc800000, v250
	v_fmac_f32_e32 v234, 0xbc800000, v250
	v_fmac_f32_e32 v235, 0xbc800000, v250
	v_fmac_f32_e32 v236, 0xbc800000, v250
	v_fmac_f32_e32 v237, 0xbc800000, v250
	v_fmac_f32_e32 v238, 0xbc800000, v250
	v_fmac_f32_e32 v239, 0xbc800000, v250
	v_fmac_f32_e32 v240, 0xbc800000, v250
	v_fmac_f32_e32 v241, 0xbc800000, v250
	v_fmac_f32_e32 v242, 0xbc800000, v250
	v_fmac_f32_e32 v243, 0xbc800000, v250
	v_mul_f32_e32 v250, v228, v228
	v_mul_f32_e32 v251, v229, v229
	v_fmac_f32_e32 v250, v230, v230
	v_fmac_f32_e32 v251, v231, v231
	v_fmac_f32_e32 v250, v232, v232
	v_fmac_f32_e32 v251, v233, v233
	v_fmac_f32_e32 v250, v234, v234
	v_fmac_f32_e32 v251, v235, v235
	v_fmac_f32_e32 v250, v236, v236
	v_fmac_f32_e32 v251, v237, v237
	v_fmac_f32_e32 v250, v238, v238
	v_fmac_f32_e32 v251, v239, v239
	v_fmac_f32_e32 v250, v240, v240
	v_fmac_f32_e32 v251, v241, v241
	v_fmac_f32_e32 v250, v242, v242
	v_fmac_f32_e32 v251, v243, v243
	v_add_f32_e32 v250, v250, v251
	v_mov_b32_e32 v251, v250
	s_nop 1
	v_permlane16_swap_b32_e32 v251, v250
	v_add_f32_e32 v250, v250, v251
	v_mov_b32_e32 v251, v250
	s_nop 1
	v_permlane32_swap_b32_e32 v251, v250
	v_add_f32_e32 v250, v250, v251
	v_fmamk_f32 v250, v250, 0x3c800000, v166
	v_mul_f32_e32 v251, 0x4b800000, v250
	v_cmp_gt_f32_e64 s[0:1], s16, v250
	s_nop 1
	v_cndmask_b32_e64 v250, v250, v251, s[0:1]
	v_rsq_f32_e32 v252, v250
	s_nop 0
	v_mul_f32_e32 v251, 0x45800000, v252
	v_cndmask_b32_e64 v252, v252, v251, s[0:1]
	v_mul_f32_e32 v228, v228, v252
	v_fma_f32 v228, v228, v194, v210
	v_lshlrev_b32_e32 v244, 16, v158
	v_fmac_f32_e32 v228, v147, v244
	v_mul_f32_e32 v228, v78, v228
	v_mul_f32_e32 v229, v229, v252
	v_fma_f32 v229, v229, v195, v211
	v_and_b32_e32 v244, 0xffff0000, v158
	v_fmac_f32_e32 v229, v147, v244
	v_mul_f32_e32 v229, v79, v229
	v_mul_f32_e32 v230, v230, v252
	v_fma_f32 v230, v230, v196, v212
	v_lshlrev_b32_e32 v244, 16, v159
	v_fmac_f32_e32 v230, v147, v244
	v_mul_f32_e32 v230, v80, v230
	v_mul_f32_e32 v231, v231, v252
	v_fma_f32 v231, v231, v197, v213
	v_and_b32_e32 v244, 0xffff0000, v159
	v_fmac_f32_e32 v231, v147, v244
	v_mul_f32_e32 v231, v81, v231
	v_mul_f32_e32 v232, v232, v252
	v_fma_f32 v232, v232, v198, v214
	v_lshlrev_b32_e32 v244, 16, v160
	v_fmac_f32_e32 v232, v147, v244
	v_mul_f32_e32 v232, v74, v232
	v_mul_f32_e32 v233, v233, v252
	v_fma_f32 v233, v233, v199, v215
	v_and_b32_e32 v244, 0xffff0000, v160
	v_fmac_f32_e32 v233, v147, v244
	v_mul_f32_e32 v233, v75, v233
	v_mul_f32_e32 v234, v234, v252
	v_fma_f32 v234, v234, v200, v216
	v_lshlrev_b32_e32 v244, 16, v161
	v_fmac_f32_e32 v234, v147, v244
	v_mul_f32_e32 v234, v76, v234
	v_mul_f32_e32 v235, v235, v252
	v_fma_f32 v235, v235, v201, v217
	v_and_b32_e32 v244, 0xffff0000, v161
	v_fmac_f32_e32 v235, v147, v244
	v_mul_f32_e32 v235, v77, v235
	v_mul_f32_e32 v236, v236, v252
	v_fma_f32 v236, v236, v202, v218
	v_lshlrev_b32_e32 v244, 16, v162
	v_fmac_f32_e32 v236, v147, v244
	v_mul_f32_e32 v236, v70, v236
	v_mul_f32_e32 v237, v237, v252
	v_fma_f32 v237, v237, v203, v219
	v_and_b32_e32 v244, 0xffff0000, v162
	v_fmac_f32_e32 v237, v147, v244
	v_mul_f32_e32 v237, v71, v237
	v_mul_f32_e32 v238, v238, v252
	v_fma_f32 v238, v238, v204, v220
	v_lshlrev_b32_e32 v244, 16, v163
	v_fmac_f32_e32 v238, v147, v244
	v_mul_f32_e32 v238, v72, v238
	v_mul_f32_e32 v239, v239, v252
	v_fma_f32 v239, v239, v205, v221
	v_and_b32_e32 v244, 0xffff0000, v163
	v_fmac_f32_e32 v239, v147, v244
	v_mul_f32_e32 v239, v73, v239
	v_mul_f32_e32 v240, v240, v252
	v_fma_f32 v240, v240, v206, v222
	v_lshlrev_b32_e32 v244, 16, v164
	v_fmac_f32_e32 v240, v147, v244
	v_mul_f32_e32 v240, v66, v240
	v_mul_f32_e32 v241, v241, v252
	v_fma_f32 v241, v241, v207, v223
	v_and_b32_e32 v244, 0xffff0000, v164
	v_fmac_f32_e32 v241, v147, v244
	v_mul_f32_e32 v241, v67, v241
	v_mul_f32_e32 v242, v242, v252
	v_fma_f32 v242, v242, v208, v224
	v_lshlrev_b32_e32 v244, 16, v165
	v_fmac_f32_e32 v242, v147, v244
	v_mul_f32_e32 v242, v68, v242
	v_mul_f32_e32 v243, v243, v252
	v_fma_f32 v243, v243, v209, v225
	v_and_b32_e32 v244, 0xffff0000, v165
	v_fmac_f32_e32 v243, v147, v244
	v_mul_f32_e32 v243, v69, v243
	v_cvt_pk_bf16_f32 v228, v228, v229
	v_cvt_pk_bf16_f32 v229, v230, v231
	v_cvt_pk_bf16_f32 v230, v232, v233
	v_cvt_pk_bf16_f32 v231, v234, v235
	v_cvt_pk_bf16_f32 v232, v236, v237
	v_cvt_pk_bf16_f32 v233, v238, v239
	v_cvt_pk_bf16_f32 v234, v240, v241
	v_cvt_pk_bf16_f32 v235, v242, v243
	s_nop 1
	v_permlane16_swap_b32_e32 v228, v230
	v_permlane16_swap_b32_e32 v229, v231
	v_permlane16_swap_b32_e32 v232, v234
	v_permlane16_swap_b32_e32 v233, v235
	v_mov_b64_e32 v[248:249], v[226:227]
	s_add_i32 s0, s19, 80
	v_add_u32_e32 v253, s0, v0
	v_cmp_gt_i32_e32 vcc, s14, v253
	s_nop 1
	v_cndmask_b32_e32 v253, v168, v253, vcc
	v_mov_b64_e32 v[226:227], s[88:89]
	v_mad_i64_i32 v[226:227], s[0:1], v253, s15, v[226:227]
	v_mov_b32_e32 v244, v254
	v_mov_b32_e32 v245, 0
	v_lshl_add_u64 v[226:227], v[226:227], 0, v[244:245]
	global_load_dwordx4 v[150:153], v[226:227], off offset:0
	global_load_dwordx4 v[154:157], v[226:227], off offset:64
	v_ashrrev_i32_e32 v251, 31, v253
	v_mov_b32_e32 v250, v253
	v_lshlrev_b64 v[246:247], 11, v[250:251]
	v_lshl_add_u64 v[246:247], s[54:55], 0, v[246:247]
	v_lshl_add_u64 v[246:247], v[246:247], 0, v[244:245]
	global_load_dwordx4 v[158:161], v[246:247], off offset:0
	global_load_dwordx4 v[162:165], v[246:247], off offset:64
	v_lshlrev_b64 v[246:247], 6, v[250:251]
	v_lshl_add_u64 v[246:247], s[58:59], 0, v[246:247]
	v_lshl_add_u64 v[246:247], v[246:247], 0, s[20:21]
	global_load_dword v147, v[246:247], off
	s_add_i32 s0, s19, 48
	v_add_u32_e32 v253, s0, v0
	v_cmp_gt_i32_e32 vcc, s14, v253
	s_and_saveexec_b64 s[0:1], vcc
	global_store_dwordx4 v[248:249], v[228:231], off offset:0
	global_store_dwordx4 v[248:249], v[232:235], off offset:64
	s_or_b64 exec, exec, s[0:1]
	s_waitcnt vmcnt(5)
	v_permlane16_swap_b32_e32 v130, v132
	v_permlane16_swap_b32_e32 v131, v133
	v_permlane16_swap_b32_e32 v134, v136
	v_permlane16_swap_b32_e32 v135, v137
	v_permlane16_swap_b32_e32 v138, v140
	v_permlane16_swap_b32_e32 v139, v141
	v_permlane16_swap_b32_e32 v142, v144
	v_permlane16_swap_b32_e32 v143, v145
	v_lshlrev_b32_e32 v228, 16, v130
	v_and_b32_e32 v229, 0xffff0000, v130
	v_lshlrev_b32_e32 v230, 16, v131
	v_and_b32_e32 v231, 0xffff0000, v131
	v_lshlrev_b32_e32 v232, 16, v132
	v_and_b32_e32 v233, 0xffff0000, v132
	v_lshlrev_b32_e32 v234, 16, v133
	v_and_b32_e32 v235, 0xffff0000, v133
	v_lshlrev_b32_e32 v236, 16, v134
	v_and_b32_e32 v237, 0xffff0000, v134
	v_lshlrev_b32_e32 v238, 16, v135
	v_and_b32_e32 v239, 0xffff0000, v135
	v_lshlrev_b32_e32 v240, 16, v136
	v_and_b32_e32 v241, 0xffff0000, v136
	v_lshlrev_b32_e32 v242, 16, v137
	v_and_b32_e32 v243, 0xffff0000, v137
	v_add_f32_e32 v250, v228, v229
	v_add_f32_e32 v251, v230, v231
	v_add_f32_e32 v250, v250, v232
	v_add_f32_e32 v251, v251, v233
	v_add_f32_e32 v250, v250, v234
	v_add_f32_e32 v251, v251, v235
	v_add_f32_e32 v250, v250, v236
	v_add_f32_e32 v251, v251, v237
	v_add_f32_e32 v250, v250, v238
	v_add_f32_e32 v251, v251, v239
	v_add_f32_e32 v250, v250, v240
	v_add_f32_e32 v251, v251, v241
	v_add_f32_e32 v250, v250, v242
	v_add_f32_e32 v251, v251, v243
	v_add_f32_e32 v250, v250, v251
	v_mov_b32_e32 v251, v250
	s_nop 1
	v_permlane16_swap_b32_e32 v251, v250
	v_add_f32_e32 v250, v250, v251
	v_mov_b32_e32 v251, v250
	s_nop 1
	v_permlane32_swap_b32_e32 v251, v250
	v_add_f32_e32 v250, v250, v251
	v_fmac_f32_e32 v228, 0xbc800000, v250
	v_fmac_f32_e32 v229, 0xbc800000, v250
	v_fmac_f32_e32 v230, 0xbc800000, v250
	v_fmac_f32_e32 v231, 0xbc800000, v250
	v_fmac_f32_e32 v232, 0xbc800000, v250
	v_fmac_f32_e32 v233, 0xbc800000, v250
	v_fmac_f32_e32 v234, 0xbc800000, v250
	v_fmac_f32_e32 v235, 0xbc800000, v250
	v_fmac_f32_e32 v236, 0xbc800000, v250
	v_fmac_f32_e32 v237, 0xbc800000, v250
	v_fmac_f32_e32 v238, 0xbc800000, v250
	v_fmac_f32_e32 v239, 0xbc800000, v250
	v_fmac_f32_e32 v240, 0xbc800000, v250
	v_fmac_f32_e32 v241, 0xbc800000, v250
	v_fmac_f32_e32 v242, 0xbc800000, v250
	v_fmac_f32_e32 v243, 0xbc800000, v250
	v_mul_f32_e32 v250, v228, v228
	v_mul_f32_e32 v251, v229, v229
	v_fmac_f32_e32 v250, v230, v230
	v_fmac_f32_e32 v251, v231, v231
	v_fmac_f32_e32 v250, v232, v232
	v_fmac_f32_e32 v251, v233, v233
	v_fmac_f32_e32 v250, v234, v234
	v_fmac_f32_e32 v251, v235, v235
	v_fmac_f32_e32 v250, v236, v236
	v_fmac_f32_e32 v251, v237, v237
	v_fmac_f32_e32 v250, v238, v238
	v_fmac_f32_e32 v251, v239, v239
	v_fmac_f32_e32 v250, v240, v240
	v_fmac_f32_e32 v251, v241, v241
	v_fmac_f32_e32 v250, v242, v242
	v_fmac_f32_e32 v251, v243, v243
	v_add_f32_e32 v250, v250, v251
	v_mov_b32_e32 v251, v250
	s_nop 1
	v_permlane16_swap_b32_e32 v251, v250
	v_add_f32_e32 v250, v250, v251
	v_mov_b32_e32 v251, v250
	s_nop 1
	v_permlane32_swap_b32_e32 v251, v250
	v_add_f32_e32 v250, v250, v251
	v_fmamk_f32 v250, v250, 0x3c800000, v166
	v_mul_f32_e32 v251, 0x4b800000, v250
	v_cmp_gt_f32_e64 s[0:1], s16, v250
	s_nop 1
	v_cndmask_b32_e64 v250, v250, v251, s[0:1]
	v_rsq_f32_e32 v252, v250
	s_nop 0
	v_mul_f32_e32 v251, 0x45800000, v252
	v_cndmask_b32_e64 v252, v252, v251, s[0:1]
	v_mul_f32_e32 v228, v228, v252
	v_fma_f32 v228, v228, v194, v210
	v_lshlrev_b32_e32 v244, 16, v138
	v_fmac_f32_e32 v228, v146, v244
	v_mul_f32_e32 v228, v62, v228
	v_mul_f32_e32 v229, v229, v252
	v_fma_f32 v229, v229, v195, v211
	v_and_b32_e32 v244, 0xffff0000, v138
	v_fmac_f32_e32 v229, v146, v244
	v_mul_f32_e32 v229, v63, v229
	v_mul_f32_e32 v230, v230, v252
	v_fma_f32 v230, v230, v196, v212
	v_lshlrev_b32_e32 v244, 16, v139
	v_fmac_f32_e32 v230, v146, v244
	v_mul_f32_e32 v230, v64, v230
	v_mul_f32_e32 v231, v231, v252
	v_fma_f32 v231, v231, v197, v213
	v_and_b32_e32 v244, 0xffff0000, v139
	v_fmac_f32_e32 v231, v146, v244
	v_mul_f32_e32 v231, v65, v231
	v_mul_f32_e32 v232, v232, v252
	v_fma_f32 v232, v232, v198, v214
	v_lshlrev_b32_e32 v244, 16, v140
	v_fmac_f32_e32 v232, v146, v244
	v_mul_f32_e32 v232, v58, v232
	v_mul_f32_e32 v233, v233, v252
	v_fma_f32 v233, v233, v199, v215
	v_and_b32_e32 v244, 0xffff0000, v140
	v_fmac_f32_e32 v233, v146, v244
	v_mul_f32_e32 v233, v59, v233
	v_mul_f32_e32 v234, v234, v252
	v_fma_f32 v234, v234, v200, v216
	v_lshlrev_b32_e32 v244, 16, v141
	v_fmac_f32_e32 v234, v146, v244
	v_mul_f32_e32 v234, v60, v234
	v_mul_f32_e32 v235, v235, v252
	v_fma_f32 v235, v235, v201, v217
	v_and_b32_e32 v244, 0xffff0000, v141
	v_fmac_f32_e32 v235, v146, v244
	v_mul_f32_e32 v235, v61, v235
	v_mul_f32_e32 v236, v236, v252
	v_fma_f32 v236, v236, v202, v218
	v_lshlrev_b32_e32 v244, 16, v142
	v_fmac_f32_e32 v236, v146, v244
	v_mul_f32_e32 v236, v54, v236
	v_mul_f32_e32 v237, v237, v252
	v_fma_f32 v237, v237, v203, v219
	v_and_b32_e32 v244, 0xffff0000, v142
	v_fmac_f32_e32 v237, v146, v244
	v_mul_f32_e32 v237, v55, v237
	v_mul_f32_e32 v238, v238, v252
	v_fma_f32 v238, v238, v204, v220
	v_lshlrev_b32_e32 v244, 16, v143
	v_fmac_f32_e32 v238, v146, v244
	v_mul_f32_e32 v238, v56, v238
	v_mul_f32_e32 v239, v239, v252
	v_fma_f32 v239, v239, v205, v221
	v_and_b32_e32 v244, 0xffff0000, v143
	v_fmac_f32_e32 v239, v146, v244
	v_mul_f32_e32 v239, v57, v239
	v_mul_f32_e32 v240, v240, v252
	v_fma_f32 v240, v240, v206, v222
	v_lshlrev_b32_e32 v244, 16, v144
	v_fmac_f32_e32 v240, v146, v244
	v_mul_f32_e32 v240, v50, v240
	v_mul_f32_e32 v241, v241, v252
	v_fma_f32 v241, v241, v207, v223
	v_and_b32_e32 v244, 0xffff0000, v144
	v_fmac_f32_e32 v241, v146, v244
	v_mul_f32_e32 v241, v51, v241
	v_mul_f32_e32 v242, v242, v252
	v_fma_f32 v242, v242, v208, v224
	v_lshlrev_b32_e32 v244, 16, v145
	v_fmac_f32_e32 v242, v146, v244
	v_mul_f32_e32 v242, v52, v242
	v_mul_f32_e32 v243, v243, v252
	v_fma_f32 v243, v243, v209, v225
	v_and_b32_e32 v244, 0xffff0000, v145
	v_fmac_f32_e32 v243, v146, v244
	v_mul_f32_e32 v243, v53, v243
	v_cvt_pk_bf16_f32 v228, v228, v229
	v_cvt_pk_bf16_f32 v229, v230, v231
	v_cvt_pk_bf16_f32 v230, v232, v233
	v_cvt_pk_bf16_f32 v231, v234, v235
	v_cvt_pk_bf16_f32 v232, v236, v237
	v_cvt_pk_bf16_f32 v233, v238, v239
	v_cvt_pk_bf16_f32 v234, v240, v241
	v_cvt_pk_bf16_f32 v235, v242, v243
	s_nop 1
	v_permlane16_swap_b32_e32 v228, v230
	v_permlane16_swap_b32_e32 v229, v231
	v_permlane16_swap_b32_e32 v232, v234
	v_permlane16_swap_b32_e32 v233, v235
	v_mov_b64_e32 v[248:249], v[148:149]
	s_add_i32 s0, s19, 96
	v_add_u32_e32 v253, s0, v0
	v_cmp_gt_i32_e32 vcc, s14, v253
	s_nop 1
	v_cndmask_b32_e32 v253, v168, v253, vcc
	v_mov_b64_e32 v[148:149], s[88:89]
	v_mad_i64_i32 v[148:149], s[0:1], v253, s15, v[148:149]
	v_mov_b32_e32 v244, v254
	v_mov_b32_e32 v245, 0
	v_lshl_add_u64 v[148:149], v[148:149], 0, v[244:245]
	global_load_dwordx4 v[130:133], v[148:149], off offset:0
	global_load_dwordx4 v[134:137], v[148:149], off offset:64
	v_ashrrev_i32_e32 v251, 31, v253
	v_mov_b32_e32 v250, v253
	v_lshlrev_b64 v[246:247], 11, v[250:251]
	v_lshl_add_u64 v[246:247], s[54:55], 0, v[246:247]
	v_lshl_add_u64 v[246:247], v[246:247], 0, v[244:245]
	global_load_dwordx4 v[138:141], v[246:247], off offset:0
	global_load_dwordx4 v[142:145], v[246:247], off offset:64
	v_lshlrev_b64 v[246:247], 6, v[250:251]
	v_lshl_add_u64 v[246:247], s[58:59], 0, v[246:247]
	v_lshl_add_u64 v[246:247], v[246:247], 0, s[20:21]
	global_load_dword v146, v[246:247], off
	s_add_i32 s0, s19, 64
	v_add_u32_e32 v253, s0, v0
	v_cmp_gt_i32_e32 vcc, s14, v253
	s_and_saveexec_b64 s[0:1], vcc
	global_store_dwordx4 v[248:249], v[228:231], off offset:0
	global_store_dwordx4 v[248:249], v[232:235], off offset:64
	s_or_b64 exec, exec, s[0:1]
	s_waitcnt vmcnt(5)
	v_permlane16_swap_b32_e32 v150, v152
	v_permlane16_swap_b32_e32 v151, v153
	v_permlane16_swap_b32_e32 v154, v156
	v_permlane16_swap_b32_e32 v155, v157
	v_permlane16_swap_b32_e32 v158, v160
	v_permlane16_swap_b32_e32 v159, v161
	v_permlane16_swap_b32_e32 v162, v164
	v_permlane16_swap_b32_e32 v163, v165
	v_lshlrev_b32_e32 v228, 16, v150
	v_and_b32_e32 v229, 0xffff0000, v150
	v_lshlrev_b32_e32 v230, 16, v151
	v_and_b32_e32 v231, 0xffff0000, v151
	v_lshlrev_b32_e32 v232, 16, v152
	v_and_b32_e32 v233, 0xffff0000, v152
	v_lshlrev_b32_e32 v234, 16, v153
	v_and_b32_e32 v235, 0xffff0000, v153
	v_lshlrev_b32_e32 v236, 16, v154
	v_and_b32_e32 v237, 0xffff0000, v154
	v_lshlrev_b32_e32 v238, 16, v155
	v_and_b32_e32 v239, 0xffff0000, v155
	v_lshlrev_b32_e32 v240, 16, v156
	v_and_b32_e32 v241, 0xffff0000, v156
	v_lshlrev_b32_e32 v242, 16, v157
	v_and_b32_e32 v243, 0xffff0000, v157
	v_add_f32_e32 v250, v228, v229
	v_add_f32_e32 v251, v230, v231
	v_add_f32_e32 v250, v250, v232
	v_add_f32_e32 v251, v251, v233
	v_add_f32_e32 v250, v250, v234
	v_add_f32_e32 v251, v251, v235
	v_add_f32_e32 v250, v250, v236
	v_add_f32_e32 v251, v251, v237
	v_add_f32_e32 v250, v250, v238
	v_add_f32_e32 v251, v251, v239
	v_add_f32_e32 v250, v250, v240
	v_add_f32_e32 v251, v251, v241
	v_add_f32_e32 v250, v250, v242
	v_add_f32_e32 v251, v251, v243
	v_add_f32_e32 v250, v250, v251
	v_mov_b32_e32 v251, v250
	s_nop 1
	v_permlane16_swap_b32_e32 v251, v250
	v_add_f32_e32 v250, v250, v251
	v_mov_b32_e32 v251, v250
	s_nop 1
	v_permlane32_swap_b32_e32 v251, v250
	v_add_f32_e32 v250, v250, v251
	v_fmac_f32_e32 v228, 0xbc800000, v250
	v_fmac_f32_e32 v229, 0xbc800000, v250
	v_fmac_f32_e32 v230, 0xbc800000, v250
	v_fmac_f32_e32 v231, 0xbc800000, v250
	v_fmac_f32_e32 v232, 0xbc800000, v250
	v_fmac_f32_e32 v233, 0xbc800000, v250
	v_fmac_f32_e32 v234, 0xbc800000, v250
	v_fmac_f32_e32 v235, 0xbc800000, v250
	v_fmac_f32_e32 v236, 0xbc800000, v250
	v_fmac_f32_e32 v237, 0xbc800000, v250
	v_fmac_f32_e32 v238, 0xbc800000, v250
	v_fmac_f32_e32 v239, 0xbc800000, v250
	v_fmac_f32_e32 v240, 0xbc800000, v250
	v_fmac_f32_e32 v241, 0xbc800000, v250
	v_fmac_f32_e32 v242, 0xbc800000, v250
	v_fmac_f32_e32 v243, 0xbc800000, v250
	v_mul_f32_e32 v250, v228, v228
	v_mul_f32_e32 v251, v229, v229
	v_fmac_f32_e32 v250, v230, v230
	v_fmac_f32_e32 v251, v231, v231
	v_fmac_f32_e32 v250, v232, v232
	v_fmac_f32_e32 v251, v233, v233
	v_fmac_f32_e32 v250, v234, v234
	v_fmac_f32_e32 v251, v235, v235
	v_fmac_f32_e32 v250, v236, v236
	v_fmac_f32_e32 v251, v237, v237
	v_fmac_f32_e32 v250, v238, v238
	v_fmac_f32_e32 v251, v239, v239
	v_fmac_f32_e32 v250, v240, v240
	v_fmac_f32_e32 v251, v241, v241
	v_fmac_f32_e32 v250, v242, v242
	v_fmac_f32_e32 v251, v243, v243
	v_add_f32_e32 v250, v250, v251
	v_mov_b32_e32 v251, v250
	s_nop 1
	v_permlane16_swap_b32_e32 v251, v250
	v_add_f32_e32 v250, v250, v251
	v_mov_b32_e32 v251, v250
	s_nop 1
	v_permlane32_swap_b32_e32 v251, v250
	v_add_f32_e32 v250, v250, v251
	v_fmamk_f32 v250, v250, 0x3c800000, v166
	v_mul_f32_e32 v251, 0x4b800000, v250
	v_cmp_gt_f32_e64 s[0:1], s16, v250
	s_nop 1
	v_cndmask_b32_e64 v250, v250, v251, s[0:1]
	v_rsq_f32_e32 v252, v250
	s_nop 0
	v_mul_f32_e32 v251, 0x45800000, v252
	v_cndmask_b32_e64 v252, v252, v251, s[0:1]
	v_mul_f32_e32 v228, v228, v252
	v_fma_f32 v228, v228, v194, v210
	v_lshlrev_b32_e32 v244, 16, v158
	v_fmac_f32_e32 v228, v147, v244
	v_mul_f32_e32 v228, v46, v228
	v_mul_f32_e32 v229, v229, v252
	v_fma_f32 v229, v229, v195, v211
	v_and_b32_e32 v244, 0xffff0000, v158
	v_fmac_f32_e32 v229, v147, v244
	v_mul_f32_e32 v229, v47, v229
	v_mul_f32_e32 v230, v230, v252
	v_fma_f32 v230, v230, v196, v212
	v_lshlrev_b32_e32 v244, 16, v159
	v_fmac_f32_e32 v230, v147, v244
	v_mul_f32_e32 v230, v48, v230
	v_mul_f32_e32 v231, v231, v252
	v_fma_f32 v231, v231, v197, v213
	v_and_b32_e32 v244, 0xffff0000, v159
	v_fmac_f32_e32 v231, v147, v244
	v_mul_f32_e32 v231, v49, v231
	v_mul_f32_e32 v232, v232, v252
	v_fma_f32 v232, v232, v198, v214
	v_lshlrev_b32_e32 v244, 16, v160
	v_fmac_f32_e32 v232, v147, v244
	v_mul_f32_e32 v232, v42, v232
	v_mul_f32_e32 v233, v233, v252
	v_fma_f32 v233, v233, v199, v215
	v_and_b32_e32 v244, 0xffff0000, v160
	v_fmac_f32_e32 v233, v147, v244
	v_mul_f32_e32 v233, v43, v233
	v_mul_f32_e32 v234, v234, v252
	v_fma_f32 v234, v234, v200, v216
	v_lshlrev_b32_e32 v244, 16, v161
	v_fmac_f32_e32 v234, v147, v244
	v_mul_f32_e32 v234, v44, v234
	v_mul_f32_e32 v235, v235, v252
	v_fma_f32 v235, v235, v201, v217
	v_and_b32_e32 v244, 0xffff0000, v161
	v_fmac_f32_e32 v235, v147, v244
	v_mul_f32_e32 v235, v45, v235
	v_mul_f32_e32 v236, v236, v252
	v_fma_f32 v236, v236, v202, v218
	v_lshlrev_b32_e32 v244, 16, v162
	v_fmac_f32_e32 v236, v147, v244
	v_mul_f32_e32 v236, v38, v236
	v_mul_f32_e32 v237, v237, v252
	v_fma_f32 v237, v237, v203, v219
	v_and_b32_e32 v244, 0xffff0000, v162
	v_fmac_f32_e32 v237, v147, v244
	v_mul_f32_e32 v237, v39, v237
	v_mul_f32_e32 v238, v238, v252
	v_fma_f32 v238, v238, v204, v220
	v_lshlrev_b32_e32 v244, 16, v163
	v_fmac_f32_e32 v238, v147, v244
	v_mul_f32_e32 v238, v40, v238
	v_mul_f32_e32 v239, v239, v252
	v_fma_f32 v239, v239, v205, v221
	v_and_b32_e32 v244, 0xffff0000, v163
	v_fmac_f32_e32 v239, v147, v244
	v_mul_f32_e32 v239, v41, v239
	v_mul_f32_e32 v240, v240, v252
	v_fma_f32 v240, v240, v206, v222
	v_lshlrev_b32_e32 v244, 16, v164
	v_fmac_f32_e32 v240, v147, v244
	v_mul_f32_e32 v240, v34, v240
	v_mul_f32_e32 v241, v241, v252
	v_fma_f32 v241, v241, v207, v223
	v_and_b32_e32 v244, 0xffff0000, v164
	v_fmac_f32_e32 v241, v147, v244
	v_mul_f32_e32 v241, v35, v241
	v_mul_f32_e32 v242, v242, v252
	v_fma_f32 v242, v242, v208, v224
	v_lshlrev_b32_e32 v244, 16, v165
	v_fmac_f32_e32 v242, v147, v244
	v_mul_f32_e32 v242, v36, v242
	v_mul_f32_e32 v243, v243, v252
	v_fma_f32 v243, v243, v209, v225
	v_and_b32_e32 v244, 0xffff0000, v165
	v_fmac_f32_e32 v243, v147, v244
	v_mul_f32_e32 v243, v37, v243
	v_cvt_pk_bf16_f32 v228, v228, v229
	v_cvt_pk_bf16_f32 v229, v230, v231
	v_cvt_pk_bf16_f32 v230, v232, v233
	v_cvt_pk_bf16_f32 v231, v234, v235
	v_cvt_pk_bf16_f32 v232, v236, v237
	v_cvt_pk_bf16_f32 v233, v238, v239
	v_cvt_pk_bf16_f32 v234, v240, v241
	v_cvt_pk_bf16_f32 v235, v242, v243
	s_nop 1
	v_permlane16_swap_b32_e32 v228, v230
	v_permlane16_swap_b32_e32 v229, v231
	v_permlane16_swap_b32_e32 v232, v234
	v_permlane16_swap_b32_e32 v233, v235
	v_mov_b64_e32 v[248:249], v[226:227]
	s_add_i32 s0, s19, 112
	v_add_u32_e32 v253, s0, v0
	v_cmp_gt_i32_e32 vcc, s14, v253
	s_nop 1
	v_cndmask_b32_e32 v253, v168, v253, vcc
	v_mov_b64_e32 v[226:227], s[88:89]
	v_mad_i64_i32 v[226:227], s[0:1], v253, s15, v[226:227]
	v_mov_b32_e32 v244, v254
	v_mov_b32_e32 v245, 0
	v_lshl_add_u64 v[226:227], v[226:227], 0, v[244:245]
	global_load_dwordx4 v[150:153], v[226:227], off offset:0
	global_load_dwordx4 v[154:157], v[226:227], off offset:64
	v_ashrrev_i32_e32 v251, 31, v253
	v_mov_b32_e32 v250, v253
	v_lshlrev_b64 v[246:247], 11, v[250:251]
	v_lshl_add_u64 v[246:247], s[54:55], 0, v[246:247]
	v_lshl_add_u64 v[246:247], v[246:247], 0, v[244:245]
	global_load_dwordx4 v[158:161], v[246:247], off offset:0
	global_load_dwordx4 v[162:165], v[246:247], off offset:64
	v_lshlrev_b64 v[246:247], 6, v[250:251]
	v_lshl_add_u64 v[246:247], s[58:59], 0, v[246:247]
	v_lshl_add_u64 v[246:247], v[246:247], 0, s[20:21]
	global_load_dword v147, v[246:247], off
	s_add_i32 s0, s19, 80
	v_add_u32_e32 v253, s0, v0
	v_cmp_gt_i32_e32 vcc, s14, v253
	s_and_saveexec_b64 s[0:1], vcc
	global_store_dwordx4 v[248:249], v[228:231], off offset:0
	global_store_dwordx4 v[248:249], v[232:235], off offset:64
	s_or_b64 exec, exec, s[0:1]
	s_waitcnt vmcnt(5)
	v_permlane16_swap_b32_e32 v130, v132
	v_permlane16_swap_b32_e32 v131, v133
	v_permlane16_swap_b32_e32 v134, v136
	v_permlane16_swap_b32_e32 v135, v137
	v_permlane16_swap_b32_e32 v138, v140
	v_permlane16_swap_b32_e32 v139, v141
	v_permlane16_swap_b32_e32 v142, v144
	v_permlane16_swap_b32_e32 v143, v145
	v_lshlrev_b32_e32 v228, 16, v130
	v_and_b32_e32 v229, 0xffff0000, v130
	v_lshlrev_b32_e32 v230, 16, v131
	v_and_b32_e32 v231, 0xffff0000, v131
	v_lshlrev_b32_e32 v232, 16, v132
	v_and_b32_e32 v233, 0xffff0000, v132
	v_lshlrev_b32_e32 v234, 16, v133
	v_and_b32_e32 v235, 0xffff0000, v133
	v_lshlrev_b32_e32 v236, 16, v134
	v_and_b32_e32 v237, 0xffff0000, v134
	v_lshlrev_b32_e32 v238, 16, v135
	v_and_b32_e32 v239, 0xffff0000, v135
	v_lshlrev_b32_e32 v240, 16, v136
	v_and_b32_e32 v241, 0xffff0000, v136
	v_lshlrev_b32_e32 v242, 16, v137
	v_and_b32_e32 v243, 0xffff0000, v137
	v_add_f32_e32 v250, v228, v229
	v_add_f32_e32 v251, v230, v231
	v_add_f32_e32 v250, v250, v232
	v_add_f32_e32 v251, v251, v233
	v_add_f32_e32 v250, v250, v234
	v_add_f32_e32 v251, v251, v235
	v_add_f32_e32 v250, v250, v236
	v_add_f32_e32 v251, v251, v237
	v_add_f32_e32 v250, v250, v238
	v_add_f32_e32 v251, v251, v239
	v_add_f32_e32 v250, v250, v240
	v_add_f32_e32 v251, v251, v241
	v_add_f32_e32 v250, v250, v242
	v_add_f32_e32 v251, v251, v243
	v_add_f32_e32 v250, v250, v251
	v_mov_b32_e32 v251, v250
	s_nop 1
	v_permlane16_swap_b32_e32 v251, v250
	v_add_f32_e32 v250, v250, v251
	v_mov_b32_e32 v251, v250
	s_nop 1
	v_permlane32_swap_b32_e32 v251, v250
	v_add_f32_e32 v250, v250, v251
	v_fmac_f32_e32 v228, 0xbc800000, v250
	v_fmac_f32_e32 v229, 0xbc800000, v250
	v_fmac_f32_e32 v230, 0xbc800000, v250
	v_fmac_f32_e32 v231, 0xbc800000, v250
	v_fmac_f32_e32 v232, 0xbc800000, v250
	v_fmac_f32_e32 v233, 0xbc800000, v250
	v_fmac_f32_e32 v234, 0xbc800000, v250
	v_fmac_f32_e32 v235, 0xbc800000, v250
	v_fmac_f32_e32 v236, 0xbc800000, v250
	v_fmac_f32_e32 v237, 0xbc800000, v250
	v_fmac_f32_e32 v238, 0xbc800000, v250
	v_fmac_f32_e32 v239, 0xbc800000, v250
	v_fmac_f32_e32 v240, 0xbc800000, v250
	v_fmac_f32_e32 v241, 0xbc800000, v250
	v_fmac_f32_e32 v242, 0xbc800000, v250
	v_fmac_f32_e32 v243, 0xbc800000, v250
	v_mul_f32_e32 v250, v228, v228
	v_mul_f32_e32 v251, v229, v229
	v_fmac_f32_e32 v250, v230, v230
	v_fmac_f32_e32 v251, v231, v231
	v_fmac_f32_e32 v250, v232, v232
	v_fmac_f32_e32 v251, v233, v233
	v_fmac_f32_e32 v250, v234, v234
	v_fmac_f32_e32 v251, v235, v235
	v_fmac_f32_e32 v250, v236, v236
	v_fmac_f32_e32 v251, v237, v237
	v_fmac_f32_e32 v250, v238, v238
	v_fmac_f32_e32 v251, v239, v239
	v_fmac_f32_e32 v250, v240, v240
	v_fmac_f32_e32 v251, v241, v241
	v_fmac_f32_e32 v250, v242, v242
	v_fmac_f32_e32 v251, v243, v243
	v_add_f32_e32 v250, v250, v251
	v_mov_b32_e32 v251, v250
	s_nop 1
	v_permlane16_swap_b32_e32 v251, v250
	v_add_f32_e32 v250, v250, v251
	v_mov_b32_e32 v251, v250
	s_nop 1
	v_permlane32_swap_b32_e32 v251, v250
	v_add_f32_e32 v250, v250, v251
	v_fmamk_f32 v250, v250, 0x3c800000, v166
	v_mul_f32_e32 v251, 0x4b800000, v250
	v_cmp_gt_f32_e64 s[0:1], s16, v250
	s_nop 1
	v_cndmask_b32_e64 v250, v250, v251, s[0:1]
	v_rsq_f32_e32 v252, v250
	s_nop 0
	v_mul_f32_e32 v251, 0x45800000, v252
	v_cndmask_b32_e64 v252, v252, v251, s[0:1]
	v_mul_f32_e32 v228, v228, v252
	v_fma_f32 v228, v228, v194, v210
	v_lshlrev_b32_e32 v244, 16, v138
	v_fmac_f32_e32 v228, v146, v244
	v_mul_f32_e32 v228, v30, v228
	v_mul_f32_e32 v229, v229, v252
	v_fma_f32 v229, v229, v195, v211
	v_and_b32_e32 v244, 0xffff0000, v138
	v_fmac_f32_e32 v229, v146, v244
	v_mul_f32_e32 v229, v31, v229
	v_mul_f32_e32 v230, v230, v252
	v_fma_f32 v230, v230, v196, v212
	v_lshlrev_b32_e32 v244, 16, v139
	v_fmac_f32_e32 v230, v146, v244
	v_mul_f32_e32 v230, v32, v230
	v_mul_f32_e32 v231, v231, v252
	v_fma_f32 v231, v231, v197, v213
	v_and_b32_e32 v244, 0xffff0000, v139
	v_fmac_f32_e32 v231, v146, v244
	v_mul_f32_e32 v231, v33, v231
	v_mul_f32_e32 v232, v232, v252
	v_fma_f32 v232, v232, v198, v214
	v_lshlrev_b32_e32 v244, 16, v140
	v_fmac_f32_e32 v232, v146, v244
	v_mul_f32_e32 v232, v26, v232
	v_mul_f32_e32 v233, v233, v252
	v_fma_f32 v233, v233, v199, v215
	v_and_b32_e32 v244, 0xffff0000, v140
	v_fmac_f32_e32 v233, v146, v244
	v_mul_f32_e32 v233, v27, v233
	v_mul_f32_e32 v234, v234, v252
	v_fma_f32 v234, v234, v200, v216
	v_lshlrev_b32_e32 v244, 16, v141
	v_fmac_f32_e32 v234, v146, v244
	v_mul_f32_e32 v234, v28, v234
	v_mul_f32_e32 v235, v235, v252
	v_fma_f32 v235, v235, v201, v217
	v_and_b32_e32 v244, 0xffff0000, v141
	v_fmac_f32_e32 v235, v146, v244
	v_mul_f32_e32 v235, v29, v235
	v_mul_f32_e32 v236, v236, v252
	v_fma_f32 v236, v236, v202, v218
	v_lshlrev_b32_e32 v244, 16, v142
	v_fmac_f32_e32 v236, v146, v244
	v_mul_f32_e32 v236, v22, v236
	v_mul_f32_e32 v237, v237, v252
	v_fma_f32 v237, v237, v203, v219
	v_and_b32_e32 v244, 0xffff0000, v142
	v_fmac_f32_e32 v237, v146, v244
	v_mul_f32_e32 v237, v23, v237
	v_mul_f32_e32 v238, v238, v252
	v_fma_f32 v238, v238, v204, v220
	v_lshlrev_b32_e32 v244, 16, v143
	v_fmac_f32_e32 v238, v146, v244
	v_mul_f32_e32 v238, v24, v238
	v_mul_f32_e32 v239, v239, v252
	v_fma_f32 v239, v239, v205, v221
	v_and_b32_e32 v244, 0xffff0000, v143
	v_fmac_f32_e32 v239, v146, v244
	v_mul_f32_e32 v239, v25, v239
	v_mul_f32_e32 v240, v240, v252
	v_fma_f32 v240, v240, v206, v222
	v_lshlrev_b32_e32 v244, 16, v144
	v_fmac_f32_e32 v240, v146, v244
	v_mul_f32_e32 v240, v18, v240
	v_mul_f32_e32 v241, v241, v252
	v_fma_f32 v241, v241, v207, v223
	v_and_b32_e32 v244, 0xffff0000, v144
	v_fmac_f32_e32 v241, v146, v244
	v_mul_f32_e32 v241, v19, v241
	v_mul_f32_e32 v242, v242, v252
	v_fma_f32 v242, v242, v208, v224
	v_lshlrev_b32_e32 v244, 16, v145
	v_fmac_f32_e32 v242, v146, v244
	v_mul_f32_e32 v242, v20, v242
	v_mul_f32_e32 v243, v243, v252
	v_fma_f32 v243, v243, v209, v225
	v_and_b32_e32 v244, 0xffff0000, v145
	v_fmac_f32_e32 v243, v146, v244
	v_mul_f32_e32 v243, v21, v243
	v_cvt_pk_bf16_f32 v228, v228, v229
	v_cvt_pk_bf16_f32 v229, v230, v231
	v_cvt_pk_bf16_f32 v230, v232, v233
	v_cvt_pk_bf16_f32 v231, v234, v235
	v_cvt_pk_bf16_f32 v232, v236, v237
	v_cvt_pk_bf16_f32 v233, v238, v239
	v_cvt_pk_bf16_f32 v234, v240, v241
	v_cvt_pk_bf16_f32 v235, v242, v243
	s_nop 1
	v_permlane16_swap_b32_e32 v228, v230
	v_permlane16_swap_b32_e32 v229, v231
	v_permlane16_swap_b32_e32 v232, v234
	v_permlane16_swap_b32_e32 v233, v235
	s_add_i32 s0, s19, 96
	v_add_u32_e32 v253, s0, v0
	v_cmp_gt_i32_e32 vcc, s14, v253
	s_and_saveexec_b64 s[0:1], vcc
	global_store_dwordx4 v[148:149], v[228:231], off offset:0
	global_store_dwordx4 v[148:149], v[232:235], off offset:64
	s_or_b64 exec, exec, s[0:1]
	s_waitcnt vmcnt(0)
	v_permlane16_swap_b32_e32 v150, v152
	v_permlane16_swap_b32_e32 v151, v153
	v_permlane16_swap_b32_e32 v154, v156
	v_permlane16_swap_b32_e32 v155, v157
	v_permlane16_swap_b32_e32 v158, v160
	v_permlane16_swap_b32_e32 v159, v161
	v_permlane16_swap_b32_e32 v162, v164
	v_permlane16_swap_b32_e32 v163, v165
	v_lshlrev_b32_e32 v228, 16, v150
	v_and_b32_e32 v229, 0xffff0000, v150
	v_lshlrev_b32_e32 v230, 16, v151
	v_and_b32_e32 v231, 0xffff0000, v151
	v_lshlrev_b32_e32 v232, 16, v152
	v_and_b32_e32 v233, 0xffff0000, v152
	v_lshlrev_b32_e32 v234, 16, v153
	v_and_b32_e32 v235, 0xffff0000, v153
	v_lshlrev_b32_e32 v236, 16, v154
	v_and_b32_e32 v237, 0xffff0000, v154
	v_lshlrev_b32_e32 v238, 16, v155
	v_and_b32_e32 v239, 0xffff0000, v155
	v_lshlrev_b32_e32 v240, 16, v156
	v_and_b32_e32 v241, 0xffff0000, v156
	v_lshlrev_b32_e32 v242, 16, v157
	v_and_b32_e32 v243, 0xffff0000, v157
	v_add_f32_e32 v250, v228, v229
	v_add_f32_e32 v251, v230, v231
	v_add_f32_e32 v250, v250, v232
	v_add_f32_e32 v251, v251, v233
	v_add_f32_e32 v250, v250, v234
	v_add_f32_e32 v251, v251, v235
	v_add_f32_e32 v250, v250, v236
	v_add_f32_e32 v251, v251, v237
	v_add_f32_e32 v250, v250, v238
	v_add_f32_e32 v251, v251, v239
	v_add_f32_e32 v250, v250, v240
	v_add_f32_e32 v251, v251, v241
	v_add_f32_e32 v250, v250, v242
	v_add_f32_e32 v251, v251, v243
	v_add_f32_e32 v250, v250, v251
	v_mov_b32_e32 v251, v250
	s_nop 1
	v_permlane16_swap_b32_e32 v251, v250
	v_add_f32_e32 v250, v250, v251
	v_mov_b32_e32 v251, v250
	s_nop 1
	v_permlane32_swap_b32_e32 v251, v250
	v_add_f32_e32 v250, v250, v251
	v_fmac_f32_e32 v228, 0xbc800000, v250
	v_fmac_f32_e32 v229, 0xbc800000, v250
	v_fmac_f32_e32 v230, 0xbc800000, v250
	v_fmac_f32_e32 v231, 0xbc800000, v250
	v_fmac_f32_e32 v232, 0xbc800000, v250
	v_fmac_f32_e32 v233, 0xbc800000, v250
	v_fmac_f32_e32 v234, 0xbc800000, v250
	v_fmac_f32_e32 v235, 0xbc800000, v250
	v_fmac_f32_e32 v236, 0xbc800000, v250
	v_fmac_f32_e32 v237, 0xbc800000, v250
	v_fmac_f32_e32 v238, 0xbc800000, v250
	v_fmac_f32_e32 v239, 0xbc800000, v250
	v_fmac_f32_e32 v240, 0xbc800000, v250
	v_fmac_f32_e32 v241, 0xbc800000, v250
	v_fmac_f32_e32 v242, 0xbc800000, v250
	v_fmac_f32_e32 v243, 0xbc800000, v250
	v_mul_f32_e32 v250, v228, v228
	v_mul_f32_e32 v251, v229, v229
	v_fmac_f32_e32 v250, v230, v230
	v_fmac_f32_e32 v251, v231, v231
	v_fmac_f32_e32 v250, v232, v232
	v_fmac_f32_e32 v251, v233, v233
	v_fmac_f32_e32 v250, v234, v234
	v_fmac_f32_e32 v251, v235, v235
	v_fmac_f32_e32 v250, v236, v236
	v_fmac_f32_e32 v251, v237, v237
	v_fmac_f32_e32 v250, v238, v238
	v_fmac_f32_e32 v251, v239, v239
	v_fmac_f32_e32 v250, v240, v240
	v_fmac_f32_e32 v251, v241, v241
	v_fmac_f32_e32 v250, v242, v242
	v_fmac_f32_e32 v251, v243, v243
	v_add_f32_e32 v250, v250, v251
	v_mov_b32_e32 v251, v250
	s_nop 1
	v_permlane16_swap_b32_e32 v251, v250
	v_add_f32_e32 v250, v250, v251
	v_mov_b32_e32 v251, v250
	s_nop 1
	v_permlane32_swap_b32_e32 v251, v250
	v_add_f32_e32 v250, v250, v251
	v_fmamk_f32 v250, v250, 0x3c800000, v166
	v_mul_f32_e32 v251, 0x4b800000, v250
	v_cmp_gt_f32_e64 s[0:1], s16, v250
	s_nop 1
	v_cndmask_b32_e64 v250, v250, v251, s[0:1]
	v_rsq_f32_e32 v252, v250
	s_nop 0
	v_mul_f32_e32 v251, 0x45800000, v252
	v_cndmask_b32_e64 v252, v252, v251, s[0:1]
	v_mul_f32_e32 v228, v228, v252
	v_fma_f32 v228, v228, v194, v210
	v_lshlrev_b32_e32 v244, 16, v158
	v_fmac_f32_e32 v228, v147, v244
	v_mul_f32_e32 v228, v14, v228
	v_mul_f32_e32 v229, v229, v252
	v_fma_f32 v229, v229, v195, v211
	v_and_b32_e32 v244, 0xffff0000, v158
	v_fmac_f32_e32 v229, v147, v244
	v_mul_f32_e32 v229, v15, v229
	v_mul_f32_e32 v230, v230, v252
	v_fma_f32 v230, v230, v196, v212
	v_lshlrev_b32_e32 v244, 16, v159
	v_fmac_f32_e32 v230, v147, v244
	v_mul_f32_e32 v230, v16, v230
	v_mul_f32_e32 v231, v231, v252
	v_fma_f32 v231, v231, v197, v213
	v_and_b32_e32 v244, 0xffff0000, v159
	v_fmac_f32_e32 v231, v147, v244
	v_mul_f32_e32 v231, v17, v231
	v_mul_f32_e32 v232, v232, v252
	v_fma_f32 v232, v232, v198, v214
	v_lshlrev_b32_e32 v244, 16, v160
	v_fmac_f32_e32 v232, v147, v244
	v_mul_f32_e32 v232, v10, v232
	v_mul_f32_e32 v233, v233, v252
	v_fma_f32 v233, v233, v199, v215
	v_and_b32_e32 v244, 0xffff0000, v160
	v_fmac_f32_e32 v233, v147, v244
	v_mul_f32_e32 v233, v11, v233
	v_mul_f32_e32 v234, v234, v252
	v_fma_f32 v234, v234, v200, v216
	v_lshlrev_b32_e32 v244, 16, v161
	v_fmac_f32_e32 v234, v147, v244
	v_mul_f32_e32 v234, v12, v234
	v_mul_f32_e32 v235, v235, v252
	v_fma_f32 v235, v235, v201, v217
	v_and_b32_e32 v244, 0xffff0000, v161
	v_fmac_f32_e32 v235, v147, v244
	v_mul_f32_e32 v235, v13, v235
	v_mul_f32_e32 v236, v236, v252
	v_fma_f32 v236, v236, v202, v218
	v_lshlrev_b32_e32 v244, 16, v162
	v_fmac_f32_e32 v236, v147, v244
	v_mul_f32_e32 v236, v6, v236
	v_mul_f32_e32 v237, v237, v252
	v_fma_f32 v237, v237, v203, v219
	v_and_b32_e32 v244, 0xffff0000, v162
	v_fmac_f32_e32 v237, v147, v244
	v_mul_f32_e32 v237, v7, v237
	v_mul_f32_e32 v238, v238, v252
	v_fma_f32 v238, v238, v204, v220
	v_lshlrev_b32_e32 v244, 16, v163
	v_fmac_f32_e32 v238, v147, v244
	v_mul_f32_e32 v238, v8, v238
	v_mul_f32_e32 v239, v239, v252
	v_fma_f32 v239, v239, v205, v221
	v_and_b32_e32 v244, 0xffff0000, v163
	v_fmac_f32_e32 v239, v147, v244
	v_mul_f32_e32 v239, v9, v239
	v_mul_f32_e32 v240, v240, v252
	v_fma_f32 v240, v240, v206, v222
	v_lshlrev_b32_e32 v244, 16, v164
	v_fmac_f32_e32 v240, v147, v244
	v_mul_f32_e32 v240, v2, v240
	v_mul_f32_e32 v241, v241, v252
	v_fma_f32 v241, v241, v207, v223
	v_and_b32_e32 v244, 0xffff0000, v164
	v_fmac_f32_e32 v241, v147, v244
	v_mul_f32_e32 v241, v3, v241
	v_mul_f32_e32 v242, v242, v252
	v_fma_f32 v242, v242, v208, v224
	v_lshlrev_b32_e32 v244, 16, v165
	v_fmac_f32_e32 v242, v147, v244
	v_mul_f32_e32 v242, v4, v242
	v_mul_f32_e32 v243, v243, v252
	v_fma_f32 v243, v243, v209, v225
	v_and_b32_e32 v244, 0xffff0000, v165
	v_fmac_f32_e32 v243, v147, v244
	v_mul_f32_e32 v243, v5, v243
	v_cvt_pk_bf16_f32 v228, v228, v229
	v_cvt_pk_bf16_f32 v229, v230, v231
	v_cvt_pk_bf16_f32 v230, v232, v233
	v_cvt_pk_bf16_f32 v231, v234, v235
	v_cvt_pk_bf16_f32 v232, v236, v237
	v_cvt_pk_bf16_f32 v233, v238, v239
	v_cvt_pk_bf16_f32 v234, v240, v241
	v_cvt_pk_bf16_f32 v235, v242, v243
	s_nop 1
	v_permlane16_swap_b32_e32 v228, v230
	v_permlane16_swap_b32_e32 v229, v231
	v_permlane16_swap_b32_e32 v232, v234
	v_permlane16_swap_b32_e32 v233, v235
	s_add_i32 s0, s19, 112
	v_add_u32_e32 v253, s0, v0
	v_cmp_gt_i32_e32 vcc, s14, v253
	s_and_saveexec_b64 s[0:1], vcc
	global_store_dwordx4 v[226:227], v[228:231], off offset:0
	global_store_dwordx4 v[226:227], v[232:235], off offset:64
	s_or_b64 exec, exec, s[0:1]
	s_mov_b64 s[0:1], exec
	s_branch .LBB0_1246
